# grid-barrier XCD leader releases local workgroups before its own buffer_inv, on top of EpiResid prefetch
# baseline (speedup 1.0000x reference)
; __device__ __forceinline__ unsigned xb_ld(unsigned* p)              { return __hip_atomic_load(p, __ATOMIC_RELAXED, __HIP_MEMORY_SCOPE_AGENT); }
; __device__ __forceinline__ unsigned xb_add(unsigned* p, unsigned v) { return __hip_atomic_fetch_add(p, v, __ATOMIC_RELAXED, __HIP_MEMORY_SCOPE_AGENT); }
; #define XB_SPIN(cond, bar) do { unsigned _sp = 0; while (cond) { __builtin_amdgcn_s_sleep(1); \
;     if ((++_sp & 255u) == 0u) { if (xb_ld(&(bar)[XB_TMO])) break; if (_sp > XB_SPIN_CAP) { atomicAdd(&(bar)[XB_TMO], 1u); break; } } } } while (0)
; __device__ __forceinline__ void xcd_barrier(const XcdBarrier& b, const int tid0) {
;     ...
;             __builtin_amdgcn_fence(__ATOMIC_RELEASE, "agent");
;             asm volatile("s_waitcnt vmcnt(0)" ::: "memory");
;             const unsigned og = xb_add(&bar[XB_TOP], 1u);
;             const unsigned tg = og / nx;
;             if (og + 1u == (tg + 1u) * nx) xb_add(&bar[XB_TOPGEN], 1u);
;             else XB_SPIN(xb_ld(&bar[XB_TOPGEN]) == tg, bar);
;             __builtin_amdgcn_fence(__ATOMIC_ACQUIRE, "agent");
;             xb_add(&bar[XB_XGEN(bx_)], 1u);
;             asm volatile("s_waitcnt vmcnt(0)" ::: "memory");
.LBB0_169:
	s_or_b64 exec, exec, s[6:7]
	s_add_i32 s30, s9, 0x900
	s_lshl_b64 s[6:7], s[30:31], 2
	s_add_u32 s4, s4, s6
	s_addc_u32 s5, s5, s7
	v_mov_b64_e32 v[0:1], s[4:5]
	s_waitcnt vmcnt(0) lgkmcnt(0)
	flat_atomic_add v[0:1], v230
	buffer_inv sc1
	s_waitcnt vmcnt(0)

; __device__ __forceinline__ unsigned xb_ld(unsigned* p)              { return __hip_atomic_load(p, __ATOMIC_RELAXED, __HIP_MEMORY_SCOPE_AGENT); }
; __device__ __forceinline__ unsigned xb_add(unsigned* p, unsigned v) { return __hip_atomic_fetch_add(p, v, __ATOMIC_RELAXED, __HIP_MEMORY_SCOPE_AGENT); }
; #define XB_SPIN(cond, bar) do { unsigned _sp = 0; while (cond) { __builtin_amdgcn_s_sleep(1); \
;     if ((++_sp & 255u) == 0u) { if (xb_ld(&(bar)[XB_TMO])) break; if (_sp > XB_SPIN_CAP) { atomicAdd(&(bar)[XB_TMO], 1u); break; } } } } while (0)
; __device__ __forceinline__ void xcd_barrier(const XcdBarrier& b, const int tid0) {
;     ...
;             __builtin_amdgcn_fence(__ATOMIC_RELEASE, "agent");
;             asm volatile("s_waitcnt vmcnt(0)" ::: "memory");
;             const unsigned og = xb_add(&bar[XB_TOP], 1u);
;             const unsigned tg = og / nx;
;             if (og + 1u == (tg + 1u) * nx) xb_add(&bar[XB_TOPGEN], 1u);
;             else XB_SPIN(xb_ld(&bar[XB_TOPGEN]) == tg, bar);
;             __builtin_amdgcn_fence(__ATOMIC_ACQUIRE, "agent");
;             xb_add(&bar[XB_XGEN(bx_)], 1u);
;             asm volatile("s_waitcnt vmcnt(0)" ::: "memory");
.LBB0_171:
	s_or_b64 exec, exec, s[6:7]
	s_add_i32 s30, s18, 0x900
	s_lshl_b64 s[6:7], s[30:31], 2
	s_add_u32 s4, s4, s6
	s_addc_u32 s5, s5, s7
	v_mov_b64_e32 v[0:1], s[4:5]
	s_waitcnt vmcnt(0) lgkmcnt(0)
	flat_atomic_add v[0:1], v230
	buffer_inv sc1
	s_waitcnt vmcnt(0)

; __device__ __forceinline__ unsigned xb_ld(unsigned* p)              { return __hip_atomic_load(p, __ATOMIC_RELAXED, __HIP_MEMORY_SCOPE_AGENT); }
; __device__ __forceinline__ unsigned xb_add(unsigned* p, unsigned v) { return __hip_atomic_fetch_add(p, v, __ATOMIC_RELAXED, __HIP_MEMORY_SCOPE_AGENT); }
; #define XB_SPIN(cond, bar) do { unsigned _sp = 0; while (cond) { __builtin_amdgcn_s_sleep(1); \
;     if ((++_sp & 255u) == 0u) { if (xb_ld(&(bar)[XB_TMO])) break; if (_sp > XB_SPIN_CAP) { atomicAdd(&(bar)[XB_TMO], 1u); break; } } } } while (0)
; __device__ __forceinline__ void xcd_barrier(const XcdBarrier& b, const int tid0) {
;     ...
;             __builtin_amdgcn_fence(__ATOMIC_RELEASE, "agent");
;             asm volatile("s_waitcnt vmcnt(0)" ::: "memory");
;             const unsigned og = xb_add(&bar[XB_TOP], 1u);
;             const unsigned tg = og / nx;
;             if (og + 1u == (tg + 1u) * nx) xb_add(&bar[XB_TOPGEN], 1u);
;             else XB_SPIN(xb_ld(&bar[XB_TOPGEN]) == tg, bar);
;             __builtin_amdgcn_fence(__ATOMIC_ACQUIRE, "agent");
;             xb_add(&bar[XB_XGEN(bx_)], 1u);
;             asm volatile("s_waitcnt vmcnt(0)" ::: "memory");
.LBB0_243:
	s_or_b64 exec, exec, s[8:9]
	s_add_i32 s30, s18, 0x900
	s_lshl_b64 s[8:9], s[30:31], 2
	s_add_u32 s4, s4, s8
	s_addc_u32 s5, s5, s9
	v_mov_b64_e32 v[0:1], s[4:5]
	s_waitcnt vmcnt(0) lgkmcnt(0)
	flat_atomic_add v[0:1], v230
	buffer_inv sc1
	s_waitcnt vmcnt(0)
